# overlay-protecting L2 write-backs issued by one workgroup per co-XCD group/batch right after the WOA/DN0/WOB/DN1 K-loops (off the seams), XCD leader write-back dropped at seams 3,10; last-unit stores
# baseline (speedup 1.0000x reference)
.LBB0_681:
	s_add_u32 s98, s40, 0xfffc0000
	s_addc_u32 s99, s41, -1
	s_mov_b32 m0, s58
	s_nop 0
	global_load_lds_dwordx4 v138, s[98:99]
	v_add_u32_e32 v154, s62, v156
	ds_read_b128 v[130:133], v154
	ds_read_b128 v[150:153], v154 offset:1024
	ds_read_b128 v[160:163], v154 offset:2048
	ds_read_b128 v[164:167], v154 offset:3072
	v_add_u32_e32 v154, s63, v156
	ds_read_b128 v[168:171], v154
	ds_read_b128 v[172:175], v154 offset:1024
	ds_read_b128 v[180:183], v154 offset:2048
	ds_read_b128 v[184:187], v154 offset:3072
	s_add_u32 s42, s40, 0xfffc0080
	s_addc_u32 s43, s41, -1
	s_cmp_eq_u32 s68, 12
	s_cselect_b32 s45, s31, s43
	s_cselect_b32 s44, s39, s42
	s_cselect_b32 s43, s29, s67
	s_cselect_b32 s42, s65, s66
	v_lshl_add_u64 v[154:155], s[40:41], 0, v[144:145]
	s_add_i32 m0, s51, 0xc000
	ds_read_b128 v[188:191], v158
	ds_read_b128 v[192:195], v158 offset:1024
	ds_read_b128 v[196:199], v158 offset:2048
	ds_read_b128 v[200:203], v158 offset:3072
	ds_read_b128 v[204:207], v158 offset:4096
	ds_read_b128 v[208:211], v158 offset:5120
	ds_read_b128 v[212:215], v158 offset:6144
	ds_read_b128 v[216:219], v158 offset:7168
	global_load_lds_dwordx4 v[154:155], off
	v_lshl_add_u64 v[154:155], s[40:41], 0, v[142:143]
	s_add_i32 m0, s51, 0xe000
	s_nop 0
	global_load_lds_dwordx4 v[154:155], off
	s_waitcnt vmcnt(8)
	s_waitcnt lgkmcnt(0)
	v_mfma_f32_16x16x32_bf16 v[114:117], v[130:133], v[188:191], v[114:117]
	v_mfma_f32_16x16x32_bf16 v[118:121], v[160:163], v[188:191], v[118:121]
	v_mfma_f32_16x16x32_bf16 v[98:101], v[130:133], v[196:199], v[98:101]
	v_mfma_f32_16x16x32_bf16 v[102:105], v[160:163], v[196:199], v[102:105]
	s_barrier
	s_setprio 1
	v_mfma_f32_16x16x32_bf16 v[82:85], v[130:133], v[204:207], v[82:85]
	v_mfma_f32_16x16x32_bf16 v[86:89], v[160:163], v[204:207], v[86:89]
	v_mfma_f32_16x16x32_bf16 v[66:69], v[130:133], v[212:215], v[66:69]
	v_mfma_f32_16x16x32_bf16 v[70:73], v[160:163], v[212:215], v[70:73]
	v_mfma_f32_16x16x32_bf16 v[114:117], v[150:153], v[192:195], v[114:117]
	v_mfma_f32_16x16x32_bf16 v[118:121], v[164:167], v[192:195], v[118:121]
	v_mfma_f32_16x16x32_bf16 v[98:101], v[150:153], v[200:203], v[98:101]
	v_mfma_f32_16x16x32_bf16 v[102:105], v[164:167], v[200:203], v[102:105]
	v_mfma_f32_16x16x32_bf16 v[82:85], v[150:153], v[208:211], v[82:85]
	v_mfma_f32_16x16x32_bf16 v[86:89], v[164:167], v[208:211], v[86:89]
	v_mfma_f32_16x16x32_bf16 v[66:69], v[150:153], v[216:219], v[66:69]
	v_mfma_f32_16x16x32_bf16 v[70:73], v[164:167], v[216:219], v[70:73]
	v_mfma_f32_16x16x32_bf16 v[122:125], v[168:171], v[188:191], v[122:125]
	v_mfma_f32_16x16x32_bf16 v[126:129], v[180:183], v[188:191], v[126:129]
	v_mfma_f32_16x16x32_bf16 v[106:109], v[168:171], v[196:199], v[106:109]
	v_mfma_f32_16x16x32_bf16 v[110:113], v[180:183], v[196:199], v[110:113]
	v_mfma_f32_16x16x32_bf16 v[90:93], v[168:171], v[204:207], v[90:93]
	v_mfma_f32_16x16x32_bf16 v[94:97], v[180:183], v[204:207], v[94:97]
	v_mfma_f32_16x16x32_bf16 v[74:77], v[168:171], v[212:215], v[74:77]
	v_mfma_f32_16x16x32_bf16 v[78:81], v[180:183], v[212:215], v[78:81]
	v_mfma_f32_16x16x32_bf16 v[122:125], v[172:175], v[192:195], v[122:125]
	v_mfma_f32_16x16x32_bf16 v[126:129], v[184:187], v[192:195], v[126:129]
	v_mfma_f32_16x16x32_bf16 v[106:109], v[172:175], v[200:203], v[106:109]
	v_mfma_f32_16x16x32_bf16 v[110:113], v[184:187], v[200:203], v[110:113]
	v_mfma_f32_16x16x32_bf16 v[90:93], v[172:175], v[208:211], v[90:93]
	v_mfma_f32_16x16x32_bf16 v[94:97], v[184:187], v[208:211], v[94:97]
	v_mfma_f32_16x16x32_bf16 v[74:77], v[172:175], v[216:219], v[74:77]
	v_mfma_f32_16x16x32_bf16 v[78:81], v[184:187], v[216:219], v[78:81]
	s_setprio 0
	s_barrier
	s_add_i32 s69, s62, s50
	v_lshl_add_u64 v[154:155], s[42:43], 0, v[136:137]
	s_mov_b32 m0, s69
	ds_read_b128 v[188:191], v158 offset:16384
	ds_read_b128 v[192:195], v158 offset:17408
	ds_read_b128 v[196:199], v158 offset:18432
	ds_read_b128 v[200:203], v158 offset:19456
	ds_read_b128 v[204:207], v158 offset:20480
	ds_read_b128 v[208:211], v158 offset:21504
	ds_read_b128 v[212:215], v158 offset:22528
	ds_read_b128 v[216:219], v158 offset:23552
	global_load_lds_dwordx4 v[154:155], off
	s_add_i32 m0, s69, 0x2000
	s_add_u32 s70, s42, 0x40000
	v_lshl_add_u64 v[176:177], s[42:43], 0, v[140:141]
	s_addc_u32 s71, s43, 0
	s_add_i32 s69, s63, s50
	global_load_lds_dwordx4 v[176:177], off
	v_lshl_add_u64 v[220:221], s[70:71], 0, v[136:137]
	s_mov_b32 m0, s69
	v_lshl_add_u64 v[222:223], s[44:45], 0, v[138:139]
	global_load_lds_dwordx4 v[220:221], off
	v_lshl_add_u64 v[220:221], s[70:71], 0, v[140:141]
	s_add_i32 m0, s69, 0x2000
	s_nop 0
	global_load_lds_dwordx4 v[220:221], off
	v_lshl_add_u64 v[220:221], s[44:45], 0, v[134:135]
	s_mov_b32 m0, s51
	s_nop 0
	global_load_lds_dwordx4 v[220:221], off
	s_waitcnt vmcnt(7)
	s_waitcnt lgkmcnt(0)
	v_mfma_f32_16x16x32_bf16 v[50:53], v[130:133], v[188:191], v[50:53]
	v_mfma_f32_16x16x32_bf16 v[54:57], v[160:163], v[188:191], v[54:57]
	v_mfma_f32_16x16x32_bf16 v[26:29], v[130:133], v[196:199], v[26:29]
	v_mfma_f32_16x16x32_bf16 v[30:33], v[160:163], v[196:199], v[30:33]
	s_barrier
	s_setprio 1
	v_mfma_f32_16x16x32_bf16 v[18:21], v[130:133], v[204:207], v[18:21]
	v_mfma_f32_16x16x32_bf16 v[22:25], v[160:163], v[204:207], v[22:25]
	v_mfma_f32_16x16x32_bf16 v[2:5], v[130:133], v[212:215], v[2:5]
	v_mfma_f32_16x16x32_bf16 v[6:9], v[160:163], v[212:215], v[6:9]
	v_mfma_f32_16x16x32_bf16 v[50:53], v[150:153], v[192:195], v[50:53]
	v_mfma_f32_16x16x32_bf16 v[54:57], v[164:167], v[192:195], v[54:57]
	v_mfma_f32_16x16x32_bf16 v[26:29], v[150:153], v[200:203], v[26:29]
	v_mfma_f32_16x16x32_bf16 v[30:33], v[164:167], v[200:203], v[30:33]
	v_mfma_f32_16x16x32_bf16 v[18:21], v[150:153], v[208:211], v[18:21]
	v_mfma_f32_16x16x32_bf16 v[22:25], v[164:167], v[208:211], v[22:25]
	v_mfma_f32_16x16x32_bf16 v[2:5], v[150:153], v[216:219], v[2:5]
	v_mfma_f32_16x16x32_bf16 v[6:9], v[164:167], v[216:219], v[6:9]
	v_mfma_f32_16x16x32_bf16 v[58:61], v[168:171], v[188:191], v[58:61]
	v_mfma_f32_16x16x32_bf16 v[62:65], v[180:183], v[188:191], v[62:65]
	v_mfma_f32_16x16x32_bf16 v[42:45], v[168:171], v[196:199], v[42:45]
	v_mfma_f32_16x16x32_bf16 v[46:49], v[180:183], v[196:199], v[46:49]
	v_mfma_f32_16x16x32_bf16 v[34:37], v[168:171], v[204:207], v[34:37]
	v_mfma_f32_16x16x32_bf16 v[38:41], v[180:183], v[204:207], v[38:41]
	v_mfma_f32_16x16x32_bf16 v[10:13], v[168:171], v[212:215], v[10:13]
	v_mfma_f32_16x16x32_bf16 v[14:17], v[180:183], v[212:215], v[14:17]
	v_mfma_f32_16x16x32_bf16 v[58:61], v[172:175], v[192:195], v[58:61]
	v_mfma_f32_16x16x32_bf16 v[62:65], v[184:187], v[192:195], v[62:65]
	v_mfma_f32_16x16x32_bf16 v[42:45], v[172:175], v[200:203], v[42:45]
	v_mfma_f32_16x16x32_bf16 v[46:49], v[184:187], v[200:203], v[46:49]
	v_mfma_f32_16x16x32_bf16 v[34:37], v[172:175], v[208:211], v[34:37]
	v_mfma_f32_16x16x32_bf16 v[38:41], v[184:187], v[208:211], v[38:41]
	v_mfma_f32_16x16x32_bf16 v[10:13], v[172:175], v[216:219], v[10:13]
	v_mfma_f32_16x16x32_bf16 v[14:17], v[184:187], v[216:219], v[14:17]
	s_setprio 0
	s_barrier
	s_mov_b32 m0, s52
	s_nop 0
	global_load_lds_dwordx4 v138, s[44:45]
	s_add_i32 s69, 0, 0x18000
	s_add_i32 s70, 0, 0x1c000
	v_add_u32_e32 v164, s69, v156
	v_add_u32_e32 v179, s70, v156
	ds_read_b128 v[130:133], v164
	ds_read_b128 v[150:153], v164 offset:1024
	ds_read_b128 v[160:163], v164 offset:2048
	ds_read_b128 v[164:167], v164 offset:3072
	ds_read_b128 v[168:171], v179
	ds_read_b128 v[172:175], v179 offset:1024
	ds_read_b128 v[180:183], v179 offset:2048
	ds_read_b128 v[184:187], v179 offset:3072
	s_add_u32 s44, s44, 0x40000
	s_addc_u32 s45, s45, 0
	s_mov_b32 m0, s53
	v_lshl_add_u64 v[224:225], s[44:45], 0, v[134:135]
	ds_read_b128 v[188:191], v158 offset:32768
	ds_read_b128 v[192:195], v158 offset:33792
	ds_read_b128 v[196:199], v158 offset:34816
	ds_read_b128 v[200:203], v158 offset:35840
	ds_read_b128 v[204:207], v158 offset:36864
	ds_read_b128 v[208:211], v158 offset:37888
	ds_read_b128 v[212:215], v158 offset:38912
	ds_read_b128 v[216:219], v158 offset:39936
	global_load_lds_dwordx4 v[224:225], off
	v_lshl_add_u64 v[224:225], s[44:45], 0, v[138:139]
	s_mov_b32 m0, s54
	s_nop 0
	global_load_lds_dwordx4 v[224:225], off
	s_waitcnt vmcnt(8)
	s_waitcnt lgkmcnt(0)
	v_mfma_f32_16x16x32_bf16 v[114:117], v[130:133], v[188:191], v[114:117]
	v_mfma_f32_16x16x32_bf16 v[118:121], v[160:163], v[188:191], v[118:121]
	v_mfma_f32_16x16x32_bf16 v[98:101], v[130:133], v[196:199], v[98:101]
	v_mfma_f32_16x16x32_bf16 v[102:105], v[160:163], v[196:199], v[102:105]
	s_barrier
	s_setprio 1
	v_mfma_f32_16x16x32_bf16 v[82:85], v[130:133], v[204:207], v[82:85]
	v_mfma_f32_16x16x32_bf16 v[86:89], v[160:163], v[204:207], v[86:89]
	v_mfma_f32_16x16x32_bf16 v[66:69], v[130:133], v[212:215], v[66:69]
	v_mfma_f32_16x16x32_bf16 v[70:73], v[160:163], v[212:215], v[70:73]
	v_mfma_f32_16x16x32_bf16 v[114:117], v[150:153], v[192:195], v[114:117]
	v_mfma_f32_16x16x32_bf16 v[118:121], v[164:167], v[192:195], v[118:121]
	v_mfma_f32_16x16x32_bf16 v[98:101], v[150:153], v[200:203], v[98:101]
	v_mfma_f32_16x16x32_bf16 v[102:105], v[164:167], v[200:203], v[102:105]
	v_mfma_f32_16x16x32_bf16 v[82:85], v[150:153], v[208:211], v[82:85]
	v_mfma_f32_16x16x32_bf16 v[86:89], v[164:167], v[208:211], v[86:89]
	v_mfma_f32_16x16x32_bf16 v[66:69], v[150:153], v[216:219], v[66:69]
	v_mfma_f32_16x16x32_bf16 v[70:73], v[164:167], v[216:219], v[70:73]
	v_mfma_f32_16x16x32_bf16 v[122:125], v[168:171], v[188:191], v[122:125]
	v_mfma_f32_16x16x32_bf16 v[126:129], v[180:183], v[188:191], v[126:129]
	v_mfma_f32_16x16x32_bf16 v[106:109], v[168:171], v[196:199], v[106:109]
	v_mfma_f32_16x16x32_bf16 v[110:113], v[180:183], v[196:199], v[110:113]
	v_mfma_f32_16x16x32_bf16 v[90:93], v[168:171], v[204:207], v[90:93]
	v_mfma_f32_16x16x32_bf16 v[94:97], v[180:183], v[204:207], v[94:97]
	v_mfma_f32_16x16x32_bf16 v[74:77], v[168:171], v[212:215], v[74:77]
	v_mfma_f32_16x16x32_bf16 v[78:81], v[180:183], v[212:215], v[78:81]
	v_mfma_f32_16x16x32_bf16 v[122:125], v[172:175], v[192:195], v[122:125]
	v_mfma_f32_16x16x32_bf16 v[126:129], v[184:187], v[192:195], v[126:129]
	v_mfma_f32_16x16x32_bf16 v[106:109], v[172:175], v[200:203], v[106:109]
	v_mfma_f32_16x16x32_bf16 v[110:113], v[184:187], v[200:203], v[110:113]
	v_mfma_f32_16x16x32_bf16 v[90:93], v[172:175], v[208:211], v[90:93]
	v_mfma_f32_16x16x32_bf16 v[94:97], v[184:187], v[208:211], v[94:97]
	v_mfma_f32_16x16x32_bf16 v[74:77], v[172:175], v[216:219], v[74:77]
	v_mfma_f32_16x16x32_bf16 v[78:81], v[184:187], v[216:219], v[78:81]
	s_setprio 0
	s_barrier
	s_add_i32 s44, s69, s50
	v_lshl_add_u64 v[154:155], v[154:155], 0, s[22:23]
	s_mov_b32 m0, s44
	ds_read_b128 v[188:191], v158 offset:49152
	ds_read_b128 v[192:195], v158 offset:50176
	ds_read_b128 v[196:199], v158 offset:51200
	ds_read_b128 v[200:203], v158 offset:52224
	ds_read_b128 v[204:207], v158 offset:53248
	ds_read_b128 v[208:211], v158 offset:54272
	ds_read_b128 v[212:215], v158 offset:55296
	ds_read_b128 v[216:219], v158 offset:56320
	global_load_lds_dwordx4 v[154:155], off
	s_add_i32 m0, s44, 0x2000
	s_add_u32 s42, s42, 0x40080
	v_lshl_add_u64 v[154:155], v[176:177], 0, s[22:23]
	s_addc_u32 s43, s43, 0
	s_add_i32 s44, s70, s50
	global_load_lds_dwordx4 v[154:155], off
	v_lshl_add_u64 v[154:155], s[42:43], 0, v[136:137]
	s_mov_b32 m0, s44
	s_nop 0
	global_load_lds_dwordx4 v[154:155], off
	v_lshl_add_u64 v[154:155], s[42:43], 0, v[140:141]
	s_add_i32 m0, s44, 0x2000
	s_nop 0
	global_load_lds_dwordx4 v[154:155], off
	v_lshl_add_u64 v[154:155], v[220:221], 0, s[22:23]
	s_mov_b32 m0, s57
	s_nop 0
	global_load_lds_dwordx4 v[154:155], off
	s_waitcnt vmcnt(7)
	s_waitcnt lgkmcnt(0)
	v_mfma_f32_16x16x32_bf16 v[50:53], v[130:133], v[188:191], v[50:53]
	v_mfma_f32_16x16x32_bf16 v[54:57], v[160:163], v[188:191], v[54:57]
	v_mfma_f32_16x16x32_bf16 v[26:29], v[130:133], v[196:199], v[26:29]
	v_mfma_f32_16x16x32_bf16 v[30:33], v[160:163], v[196:199], v[30:33]
	s_barrier
	s_setprio 1
	v_mfma_f32_16x16x32_bf16 v[18:21], v[130:133], v[204:207], v[18:21]
	v_mfma_f32_16x16x32_bf16 v[22:25], v[160:163], v[204:207], v[22:25]
	v_mfma_f32_16x16x32_bf16 v[2:5], v[130:133], v[212:215], v[2:5]
	v_mfma_f32_16x16x32_bf16 v[6:9], v[160:163], v[212:215], v[6:9]
	v_mfma_f32_16x16x32_bf16 v[50:53], v[150:153], v[192:195], v[50:53]
	v_mfma_f32_16x16x32_bf16 v[54:57], v[164:167], v[192:195], v[54:57]
	v_mfma_f32_16x16x32_bf16 v[26:29], v[150:153], v[200:203], v[26:29]
	v_mfma_f32_16x16x32_bf16 v[30:33], v[164:167], v[200:203], v[30:33]
	v_mfma_f32_16x16x32_bf16 v[18:21], v[150:153], v[208:211], v[18:21]
	v_mfma_f32_16x16x32_bf16 v[22:25], v[164:167], v[208:211], v[22:25]
	v_mfma_f32_16x16x32_bf16 v[2:5], v[150:153], v[216:219], v[2:5]
	v_mfma_f32_16x16x32_bf16 v[6:9], v[164:167], v[216:219], v[6:9]
	v_mfma_f32_16x16x32_bf16 v[58:61], v[168:171], v[188:191], v[58:61]
	v_mfma_f32_16x16x32_bf16 v[62:65], v[180:183], v[188:191], v[62:65]
	v_mfma_f32_16x16x32_bf16 v[42:45], v[168:171], v[196:199], v[42:45]
	v_mfma_f32_16x16x32_bf16 v[46:49], v[180:183], v[196:199], v[46:49]
	v_mfma_f32_16x16x32_bf16 v[34:37], v[168:171], v[204:207], v[34:37]
	v_mfma_f32_16x16x32_bf16 v[38:41], v[180:183], v[204:207], v[38:41]
	v_mfma_f32_16x16x32_bf16 v[10:13], v[168:171], v[212:215], v[10:13]
	v_mfma_f32_16x16x32_bf16 v[14:17], v[180:183], v[212:215], v[14:17]
	v_mfma_f32_16x16x32_bf16 v[58:61], v[172:175], v[192:195], v[58:61]
	v_mfma_f32_16x16x32_bf16 v[62:65], v[184:187], v[192:195], v[62:65]
	v_mfma_f32_16x16x32_bf16 v[42:45], v[172:175], v[200:203], v[42:45]
	v_mfma_f32_16x16x32_bf16 v[46:49], v[184:187], v[200:203], v[46:49]
	v_mfma_f32_16x16x32_bf16 v[34:37], v[172:175], v[208:211], v[34:37]
	v_mfma_f32_16x16x32_bf16 v[38:41], v[184:187], v[208:211], v[38:41]
	v_mfma_f32_16x16x32_bf16 v[10:13], v[172:175], v[216:219], v[10:13]
	v_mfma_f32_16x16x32_bf16 v[14:17], v[184:187], v[216:219], v[14:17]
	s_setprio 0
	s_barrier
	s_add_i32 s68, s68, 2
	s_add_u32 s66, s66, 0x100
	s_addc_u32 s67, s67, 0
	s_add_u32 s40, s40, 0x100
	s_addc_u32 s41, s41, 0
	s_cmp_gt_u32 s68, 13
	s_cbranch_scc0 .LBB0_681
	v_readfirstlane_b32 s98, v178
	s_cmp_lt_u32 s98, 64
	s_cbranch_scc0 .Lkf_a
	v_readlane_b32 s98, v250, 0
	s_cmp_lg_u32 s98, 0
	s_cselect_b32 s98, 1, 0
	s_lshr_b32 s99, s81, 6
	s_cmp_lg_u32 s99, 0
	s_cselect_b32 s99, 1, 0
	s_and_b32 s98, s98, s99
	s_cbranch_scc1 .Lkf_a
	buffer_wbl2 sc1

.LBB0_684:
	v_lshl_add_u32 v152, s38, 8, v1
	v_ashrrev_i32_e32 v153, 31, v152
	v_lshl_or_b32 v150, s18, 8, v157
	v_lshlrev_b64 v[154:155], 11, v[152:153]
	v_ashrrev_i32_e32 v151, 31, v150
	v_lshl_add_u64 v[154:155], s[0:1], 0, v[154:155]
	v_lshl_add_u64 v[154:155], v[150:151], 1, v[154:155]
	s_andn2_b64 vcc, exec, s[6:7]
	s_mov_b64 s[38:39], -1
	v_cvt_pk_bf16_f32 v130, v114, v115
	v_cvt_pk_bf16_f32 v131, v116, v117
	v_cvt_pk_bf16_f32 v132, v118, v119
	v_cvt_pk_bf16_f32 v133, v120, v121
	s_cbranch_vccnz .LBB0_686
	global_store_dwordx4 v[154:155], v[130:133], off
	s_nop 1
	s_mov_b64 s[38:39], 0

.LBB0_688:
	v_lshl_add_u64 v[154:155], v[154:155], 0, s[26:27]
	s_mov_b64 s[38:39], -1
	s_and_b64 vcc, exec, s[6:7]
	v_cvt_pk_bf16_f32 v130, v122, v123
	v_cvt_pk_bf16_f32 v131, v124, v125
	v_cvt_pk_bf16_f32 v132, v126, v127
	v_cvt_pk_bf16_f32 v133, v128, v129
	s_cbranch_vccz .LBB0_690
	global_store_dwordx4 v[154:155], v[130:133], off
	s_nop 1
	s_mov_b64 s[38:39], 0

.LBB0_694:
	s_or_b64 exec, exec, s[40:41]
	v_or_b32_e32 v118, 16, v152
	v_ashrrev_i32_e32 v119, 31, v118
	v_lshlrev_b64 v[120:121], 11, v[118:119]
	v_lshl_add_u64 v[120:121], s[0:1], 0, v[120:121]
	v_lshl_add_u64 v[120:121], v[150:151], 1, v[120:121]
	s_mov_b64 s[40:41], -1
	s_and_b64 vcc, exec, s[6:7]
	v_cvt_pk_bf16_f32 v114, v98, v99
	s_waitcnt lgkmcnt(0)
	v_cvt_pk_bf16_f32 v115, v100, v101
	v_cvt_pk_bf16_f32 v116, v102, v103
	v_cvt_pk_bf16_f32 v117, v104, v105
	s_cbranch_vccz .LBB0_696
	global_store_dwordx4 v[120:121], v[114:117], off
	s_nop 1
	s_mov_b64 s[40:41], 0

.LBB0_698:
	v_lshl_add_u64 v[120:121], v[120:121], 0, s[26:27]
	s_mov_b64 s[40:41], -1
	s_and_b64 vcc, exec, s[6:7]
	v_cvt_pk_bf16_f32 v114, v106, v107
	v_cvt_pk_bf16_f32 v115, v108, v109
	v_cvt_pk_bf16_f32 v116, v110, v111
	v_cvt_pk_bf16_f32 v117, v112, v113
	s_cbranch_vccz .LBB0_700
	global_store_dwordx4 v[120:121], v[114:117], off
	s_nop 1
	s_mov_b64 s[40:41], 0

.LBB0_704:
	s_or_b64 exec, exec, s[40:41]
	v_or_b32_e32 v102, 32, v152
	v_ashrrev_i32_e32 v103, 31, v102
	v_lshlrev_b64 v[104:105], 11, v[102:103]
	v_lshl_add_u64 v[104:105], s[0:1], 0, v[104:105]
	v_lshl_add_u64 v[104:105], v[150:151], 1, v[104:105]
	s_mov_b64 s[40:41], -1
	s_and_b64 vcc, exec, s[6:7]
	v_cvt_pk_bf16_f32 v98, v82, v83
	s_waitcnt lgkmcnt(0)
	v_cvt_pk_bf16_f32 v99, v84, v85
	v_cvt_pk_bf16_f32 v100, v86, v87
	v_cvt_pk_bf16_f32 v101, v88, v89
	s_cbranch_vccz .LBB0_706
	global_store_dwordx4 v[104:105], v[98:101], off
	s_nop 1
	s_mov_b64 s[40:41], 0

.LBB0_708:
	v_lshl_add_u64 v[104:105], v[104:105], 0, s[26:27]
	s_mov_b64 s[40:41], -1
	s_and_b64 vcc, exec, s[6:7]
	v_cvt_pk_bf16_f32 v98, v90, v91
	v_cvt_pk_bf16_f32 v99, v92, v93
	v_cvt_pk_bf16_f32 v100, v94, v95
	v_cvt_pk_bf16_f32 v101, v96, v97
	s_cbranch_vccz .LBB0_710
	global_store_dwordx4 v[104:105], v[98:101], off
	s_nop 1
	s_mov_b64 s[40:41], 0

.LBB0_714:
	s_or_b64 exec, exec, s[40:41]
	v_or_b32_e32 v86, 48, v152
	v_ashrrev_i32_e32 v87, 31, v86
	v_lshlrev_b64 v[88:89], 11, v[86:87]
	v_lshl_add_u64 v[88:89], s[0:1], 0, v[88:89]
	v_lshl_add_u64 v[88:89], v[150:151], 1, v[88:89]
	s_mov_b64 s[40:41], -1
	s_and_b64 vcc, exec, s[6:7]
	v_cvt_pk_bf16_f32 v82, v66, v67
	s_waitcnt lgkmcnt(0)
	v_cvt_pk_bf16_f32 v83, v68, v69
	v_cvt_pk_bf16_f32 v84, v70, v71
	v_cvt_pk_bf16_f32 v85, v72, v73
	s_cbranch_vccz .LBB0_716
	global_store_dwordx4 v[88:89], v[82:85], off
	s_nop 1
	s_mov_b64 s[40:41], 0

.LBB0_718:
	v_lshl_add_u64 v[88:89], v[88:89], 0, s[26:27]
	s_mov_b64 s[40:41], -1
	s_and_b64 vcc, exec, s[6:7]
	v_cvt_pk_bf16_f32 v82, v74, v75
	v_cvt_pk_bf16_f32 v83, v76, v77
	v_cvt_pk_bf16_f32 v84, v78, v79
	v_cvt_pk_bf16_f32 v85, v80, v81
	s_cbranch_vccz .LBB0_720
	global_store_dwordx4 v[88:89], v[82:85], off
	s_nop 1
	s_mov_b64 s[40:41], 0

.LBB0_724:
	s_or_b64 exec, exec, s[40:41]
	v_add_u32_e32 v70, 0x80, v152
	v_ashrrev_i32_e32 v71, 31, v70
	v_lshlrev_b64 v[72:73], 11, v[70:71]
	v_lshl_add_u64 v[72:73], s[0:1], 0, v[72:73]
	v_lshl_add_u64 v[72:73], v[150:151], 1, v[72:73]
	s_mov_b64 s[40:41], -1
	s_and_b64 vcc, exec, s[6:7]
	v_cvt_pk_bf16_f32 v66, v50, v51
	s_waitcnt lgkmcnt(0)
	v_cvt_pk_bf16_f32 v67, v52, v53
	v_cvt_pk_bf16_f32 v68, v54, v55
	v_cvt_pk_bf16_f32 v69, v56, v57
	s_cbranch_vccz .LBB0_726
	global_store_dwordx4 v[72:73], v[66:69], off
	s_nop 1
	s_mov_b64 s[40:41], 0

.LBB0_728:
	v_lshl_add_u64 v[72:73], v[72:73], 0, s[26:27]
	s_mov_b64 s[40:41], -1
	s_and_b64 vcc, exec, s[6:7]
	v_cvt_pk_bf16_f32 v66, v58, v59
	v_cvt_pk_bf16_f32 v67, v60, v61
	v_cvt_pk_bf16_f32 v68, v62, v63
	v_cvt_pk_bf16_f32 v69, v64, v65
	s_cbranch_vccz .LBB0_730
	global_store_dwordx4 v[72:73], v[66:69], off
	s_nop 1
	s_mov_b64 s[40:41], 0

.LBB0_734:
	s_or_b64 exec, exec, s[40:41]
	v_add_u32_e32 v54, 0x90, v152
	v_ashrrev_i32_e32 v55, 31, v54
	v_lshlrev_b64 v[56:57], 11, v[54:55]
	v_lshl_add_u64 v[56:57], s[0:1], 0, v[56:57]
	v_lshl_add_u64 v[56:57], v[150:151], 1, v[56:57]
	s_mov_b64 s[40:41], -1
	s_and_b64 vcc, exec, s[6:7]
	v_cvt_pk_bf16_f32 v50, v26, v27
	s_waitcnt lgkmcnt(0)
	v_cvt_pk_bf16_f32 v51, v28, v29
	v_cvt_pk_bf16_f32 v52, v30, v31
	v_cvt_pk_bf16_f32 v53, v32, v33
	s_cbranch_vccz .LBB0_736
	global_store_dwordx4 v[56:57], v[50:53], off
	s_nop 1
	s_mov_b64 s[40:41], 0

.LBB0_738:
	v_lshl_add_u64 v[56:57], v[56:57], 0, s[26:27]
	s_mov_b64 s[40:41], -1
	s_and_b64 vcc, exec, s[6:7]
	v_cvt_pk_bf16_f32 v50, v42, v43
	v_cvt_pk_bf16_f32 v51, v44, v45
	v_cvt_pk_bf16_f32 v52, v46, v47
	v_cvt_pk_bf16_f32 v53, v48, v49
	s_cbranch_vccz .LBB0_740
	global_store_dwordx4 v[56:57], v[50:53], off
	s_nop 1
	s_mov_b64 s[40:41], 0

.LBB0_744:
	s_or_b64 exec, exec, s[40:41]
	v_add_u32_e32 v30, 0xa0, v152
	v_ashrrev_i32_e32 v31, 31, v30
	v_lshlrev_b64 v[32:33], 11, v[30:31]
	v_lshl_add_u64 v[32:33], s[0:1], 0, v[32:33]
	v_lshl_add_u64 v[32:33], v[150:151], 1, v[32:33]
	s_mov_b64 s[40:41], -1
	s_and_b64 vcc, exec, s[6:7]
	v_cvt_pk_bf16_f32 v26, v18, v19
	s_waitcnt lgkmcnt(0)
	v_cvt_pk_bf16_f32 v27, v20, v21
	v_cvt_pk_bf16_f32 v28, v22, v23
	v_cvt_pk_bf16_f32 v29, v24, v25
	s_cbranch_vccz .LBB0_746
	global_store_dwordx4 v[32:33], v[26:29], off
	s_nop 1
	s_mov_b64 s[40:41], 0

.LBB0_748:
	v_lshl_add_u64 v[32:33], v[32:33], 0, s[26:27]
	s_mov_b64 s[40:41], -1
	s_and_b64 vcc, exec, s[6:7]
	v_cvt_pk_bf16_f32 v26, v34, v35
	v_cvt_pk_bf16_f32 v27, v36, v37
	v_cvt_pk_bf16_f32 v28, v38, v39
	v_cvt_pk_bf16_f32 v29, v40, v41
	s_cbranch_vccz .LBB0_750
	global_store_dwordx4 v[32:33], v[26:29], off
	s_nop 1
	s_mov_b64 s[40:41], 0

.LBB0_754:
	s_or_b64 exec, exec, s[40:41]
	v_add_u32_e32 v22, 0xb0, v152
	v_ashrrev_i32_e32 v23, 31, v22
	v_lshlrev_b64 v[24:25], 11, v[22:23]
	v_lshl_add_u64 v[24:25], s[0:1], 0, v[24:25]
	v_lshl_add_u64 v[24:25], v[150:151], 1, v[24:25]
	s_mov_b64 s[40:41], -1
	s_and_b64 vcc, exec, s[6:7]
	v_cvt_pk_bf16_f32 v18, v2, v3
	s_waitcnt lgkmcnt(0)
	v_cvt_pk_bf16_f32 v19, v4, v5
	v_cvt_pk_bf16_f32 v20, v6, v7
	v_cvt_pk_bf16_f32 v21, v8, v9
	s_cbranch_vccz .LBB0_756
	global_store_dwordx4 v[24:25], v[18:21], off
	s_nop 1
	s_mov_b64 s[40:41], 0

.LBB0_758:
	v_lshl_add_u64 v[24:25], v[24:25], 0, s[26:27]
	s_mov_b64 s[40:41], -1
	s_and_b64 vcc, exec, s[6:7]
	v_cvt_pk_bf16_f32 v18, v10, v11
	v_cvt_pk_bf16_f32 v19, v12, v13
	v_cvt_pk_bf16_f32 v20, v14, v15
	v_cvt_pk_bf16_f32 v21, v16, v17
	s_cbranch_vccz .LBB0_760
	global_store_dwordx4 v[24:25], v[18:21], off
	s_nop 1
	s_mov_b64 s[40:41], 0

.LBB0_1817:
	s_add_u32 s98, s42, 0xfffc0000
	s_addc_u32 s99, s43, -1
	s_mov_b32 m0, s60
	s_nop 0
	global_load_lds_dwordx4 v138, s[98:99]
	v_add_u32_e32 v154, s64, v156
	ds_read_b128 v[130:133], v154
	ds_read_b128 v[150:153], v154 offset:1024
	ds_read_b128 v[160:163], v154 offset:2048
	ds_read_b128 v[164:167], v154 offset:3072
	v_add_u32_e32 v154, s65, v156
	ds_read_b128 v[168:171], v154
	ds_read_b128 v[172:175], v154 offset:1024
	ds_read_b128 v[180:183], v154 offset:2048
	ds_read_b128 v[184:187], v154 offset:3072
	s_add_u32 s44, s42, 0xfffc0080
	s_addc_u32 s45, s43, -1
	s_cmp_eq_u32 s70, 12
	s_cselect_b32 s47, s35, s45
	s_cselect_b32 s46, s41, s44
	s_cselect_b32 s45, s31, s69
	s_cselect_b32 s44, s67, s68
	v_lshl_add_u64 v[154:155], s[42:43], 0, v[144:145]
	s_add_i32 m0, s53, 0xc000
	ds_read_b128 v[188:191], v158
	ds_read_b128 v[192:195], v158 offset:1024
	ds_read_b128 v[196:199], v158 offset:2048
	ds_read_b128 v[200:203], v158 offset:3072
	ds_read_b128 v[204:207], v158 offset:4096
	ds_read_b128 v[208:211], v158 offset:5120
	ds_read_b128 v[212:215], v158 offset:6144
	ds_read_b128 v[216:219], v158 offset:7168
	global_load_lds_dwordx4 v[154:155], off
	v_lshl_add_u64 v[154:155], s[42:43], 0, v[142:143]
	s_add_i32 m0, s53, 0xe000
	s_nop 0
	global_load_lds_dwordx4 v[154:155], off
	s_waitcnt vmcnt(8)
	s_waitcnt lgkmcnt(0)
	v_mfma_f32_16x16x32_bf16 v[114:117], v[130:133], v[188:191], v[114:117]
	v_mfma_f32_16x16x32_bf16 v[118:121], v[160:163], v[188:191], v[118:121]
	v_mfma_f32_16x16x32_bf16 v[98:101], v[130:133], v[196:199], v[98:101]
	v_mfma_f32_16x16x32_bf16 v[102:105], v[160:163], v[196:199], v[102:105]
	s_barrier
	s_setprio 1
	v_mfma_f32_16x16x32_bf16 v[82:85], v[130:133], v[204:207], v[82:85]
	v_mfma_f32_16x16x32_bf16 v[86:89], v[160:163], v[204:207], v[86:89]
	v_mfma_f32_16x16x32_bf16 v[66:69], v[130:133], v[212:215], v[66:69]
	v_mfma_f32_16x16x32_bf16 v[70:73], v[160:163], v[212:215], v[70:73]
	v_mfma_f32_16x16x32_bf16 v[114:117], v[150:153], v[192:195], v[114:117]
	v_mfma_f32_16x16x32_bf16 v[118:121], v[164:167], v[192:195], v[118:121]
	v_mfma_f32_16x16x32_bf16 v[98:101], v[150:153], v[200:203], v[98:101]
	v_mfma_f32_16x16x32_bf16 v[102:105], v[164:167], v[200:203], v[102:105]
	v_mfma_f32_16x16x32_bf16 v[82:85], v[150:153], v[208:211], v[82:85]
	v_mfma_f32_16x16x32_bf16 v[86:89], v[164:167], v[208:211], v[86:89]
	v_mfma_f32_16x16x32_bf16 v[66:69], v[150:153], v[216:219], v[66:69]
	v_mfma_f32_16x16x32_bf16 v[70:73], v[164:167], v[216:219], v[70:73]
	v_mfma_f32_16x16x32_bf16 v[122:125], v[168:171], v[188:191], v[122:125]
	v_mfma_f32_16x16x32_bf16 v[126:129], v[180:183], v[188:191], v[126:129]
	v_mfma_f32_16x16x32_bf16 v[106:109], v[168:171], v[196:199], v[106:109]
	v_mfma_f32_16x16x32_bf16 v[110:113], v[180:183], v[196:199], v[110:113]
	v_mfma_f32_16x16x32_bf16 v[90:93], v[168:171], v[204:207], v[90:93]
	v_mfma_f32_16x16x32_bf16 v[94:97], v[180:183], v[204:207], v[94:97]
	v_mfma_f32_16x16x32_bf16 v[74:77], v[168:171], v[212:215], v[74:77]
	v_mfma_f32_16x16x32_bf16 v[78:81], v[180:183], v[212:215], v[78:81]
	v_mfma_f32_16x16x32_bf16 v[122:125], v[172:175], v[192:195], v[122:125]
	v_mfma_f32_16x16x32_bf16 v[126:129], v[184:187], v[192:195], v[126:129]
	v_mfma_f32_16x16x32_bf16 v[106:109], v[172:175], v[200:203], v[106:109]
	v_mfma_f32_16x16x32_bf16 v[110:113], v[184:187], v[200:203], v[110:113]
	v_mfma_f32_16x16x32_bf16 v[90:93], v[172:175], v[208:211], v[90:93]
	v_mfma_f32_16x16x32_bf16 v[94:97], v[184:187], v[208:211], v[94:97]
	v_mfma_f32_16x16x32_bf16 v[74:77], v[172:175], v[216:219], v[74:77]
	v_mfma_f32_16x16x32_bf16 v[78:81], v[184:187], v[216:219], v[78:81]
	s_setprio 0
	s_barrier
	s_add_i32 s71, s64, s52
	v_lshl_add_u64 v[154:155], s[44:45], 0, v[136:137]
	s_mov_b32 m0, s71
	ds_read_b128 v[188:191], v158 offset:16384
	ds_read_b128 v[192:195], v158 offset:17408
	ds_read_b128 v[196:199], v158 offset:18432
	ds_read_b128 v[200:203], v158 offset:19456
	ds_read_b128 v[204:207], v158 offset:20480
	ds_read_b128 v[208:211], v158 offset:21504
	ds_read_b128 v[212:215], v158 offset:22528
	ds_read_b128 v[216:219], v158 offset:23552
	global_load_lds_dwordx4 v[154:155], off
	s_add_i32 m0, s71, 0x2000
	s_add_u32 s72, s44, 0x40000
	v_lshl_add_u64 v[176:177], s[44:45], 0, v[140:141]
	s_addc_u32 s73, s45, 0
	s_add_i32 s71, s65, s52
	global_load_lds_dwordx4 v[176:177], off
	v_lshl_add_u64 v[220:221], s[72:73], 0, v[136:137]
	s_mov_b32 m0, s71
	v_lshl_add_u64 v[222:223], s[46:47], 0, v[138:139]
	global_load_lds_dwordx4 v[220:221], off
	v_lshl_add_u64 v[220:221], s[72:73], 0, v[140:141]
	s_add_i32 m0, s71, 0x2000
	s_nop 0
	global_load_lds_dwordx4 v[220:221], off
	v_lshl_add_u64 v[220:221], s[46:47], 0, v[134:135]
	s_mov_b32 m0, s53
	s_nop 0
	global_load_lds_dwordx4 v[220:221], off
	s_waitcnt vmcnt(7)
	s_waitcnt lgkmcnt(0)
	v_mfma_f32_16x16x32_bf16 v[50:53], v[130:133], v[188:191], v[50:53]
	v_mfma_f32_16x16x32_bf16 v[54:57], v[160:163], v[188:191], v[54:57]
	v_mfma_f32_16x16x32_bf16 v[26:29], v[130:133], v[196:199], v[26:29]
	v_mfma_f32_16x16x32_bf16 v[30:33], v[160:163], v[196:199], v[30:33]
	s_barrier
	s_setprio 1
	v_mfma_f32_16x16x32_bf16 v[18:21], v[130:133], v[204:207], v[18:21]
	v_mfma_f32_16x16x32_bf16 v[22:25], v[160:163], v[204:207], v[22:25]
	v_mfma_f32_16x16x32_bf16 v[2:5], v[130:133], v[212:215], v[2:5]
	v_mfma_f32_16x16x32_bf16 v[6:9], v[160:163], v[212:215], v[6:9]
	v_mfma_f32_16x16x32_bf16 v[50:53], v[150:153], v[192:195], v[50:53]
	v_mfma_f32_16x16x32_bf16 v[54:57], v[164:167], v[192:195], v[54:57]
	v_mfma_f32_16x16x32_bf16 v[26:29], v[150:153], v[200:203], v[26:29]
	v_mfma_f32_16x16x32_bf16 v[30:33], v[164:167], v[200:203], v[30:33]
	v_mfma_f32_16x16x32_bf16 v[18:21], v[150:153], v[208:211], v[18:21]
	v_mfma_f32_16x16x32_bf16 v[22:25], v[164:167], v[208:211], v[22:25]
	v_mfma_f32_16x16x32_bf16 v[2:5], v[150:153], v[216:219], v[2:5]
	v_mfma_f32_16x16x32_bf16 v[6:9], v[164:167], v[216:219], v[6:9]
	v_mfma_f32_16x16x32_bf16 v[58:61], v[168:171], v[188:191], v[58:61]
	v_mfma_f32_16x16x32_bf16 v[62:65], v[180:183], v[188:191], v[62:65]
	v_mfma_f32_16x16x32_bf16 v[42:45], v[168:171], v[196:199], v[42:45]
	v_mfma_f32_16x16x32_bf16 v[46:49], v[180:183], v[196:199], v[46:49]
	v_mfma_f32_16x16x32_bf16 v[34:37], v[168:171], v[204:207], v[34:37]
	v_mfma_f32_16x16x32_bf16 v[38:41], v[180:183], v[204:207], v[38:41]
	v_mfma_f32_16x16x32_bf16 v[10:13], v[168:171], v[212:215], v[10:13]
	v_mfma_f32_16x16x32_bf16 v[14:17], v[180:183], v[212:215], v[14:17]
	v_mfma_f32_16x16x32_bf16 v[58:61], v[172:175], v[192:195], v[58:61]
	v_mfma_f32_16x16x32_bf16 v[62:65], v[184:187], v[192:195], v[62:65]
	v_mfma_f32_16x16x32_bf16 v[42:45], v[172:175], v[200:203], v[42:45]
	v_mfma_f32_16x16x32_bf16 v[46:49], v[184:187], v[200:203], v[46:49]
	v_mfma_f32_16x16x32_bf16 v[34:37], v[172:175], v[208:211], v[34:37]
	v_mfma_f32_16x16x32_bf16 v[38:41], v[184:187], v[208:211], v[38:41]
	v_mfma_f32_16x16x32_bf16 v[10:13], v[172:175], v[216:219], v[10:13]
	v_mfma_f32_16x16x32_bf16 v[14:17], v[184:187], v[216:219], v[14:17]
	s_setprio 0
	s_barrier
	s_mov_b32 m0, s54
	s_nop 0
	global_load_lds_dwordx4 v138, s[46:47]
	s_add_i32 s71, 0, 0x18000
	s_add_i32 s72, 0, 0x1c000
	v_add_u32_e32 v164, s71, v156
	v_add_u32_e32 v179, s72, v156
	ds_read_b128 v[130:133], v164
	ds_read_b128 v[150:153], v164 offset:1024
	ds_read_b128 v[160:163], v164 offset:2048
	ds_read_b128 v[164:167], v164 offset:3072
	ds_read_b128 v[168:171], v179
	ds_read_b128 v[172:175], v179 offset:1024
	ds_read_b128 v[180:183], v179 offset:2048
	ds_read_b128 v[184:187], v179 offset:3072
	s_add_u32 s46, s46, 0x40000
	s_addc_u32 s47, s47, 0
	s_mov_b32 m0, s55
	v_lshl_add_u64 v[224:225], s[46:47], 0, v[134:135]
	ds_read_b128 v[188:191], v158 offset:32768
	ds_read_b128 v[192:195], v158 offset:33792
	ds_read_b128 v[196:199], v158 offset:34816
	ds_read_b128 v[200:203], v158 offset:35840
	ds_read_b128 v[204:207], v158 offset:36864
	ds_read_b128 v[208:211], v158 offset:37888
	ds_read_b128 v[212:215], v158 offset:38912
	ds_read_b128 v[216:219], v158 offset:39936
	global_load_lds_dwordx4 v[224:225], off
	v_lshl_add_u64 v[224:225], s[46:47], 0, v[138:139]
	s_mov_b32 m0, s56
	s_nop 0
	global_load_lds_dwordx4 v[224:225], off
	s_waitcnt vmcnt(8)
	s_waitcnt lgkmcnt(0)
	v_mfma_f32_16x16x32_bf16 v[114:117], v[130:133], v[188:191], v[114:117]
	v_mfma_f32_16x16x32_bf16 v[118:121], v[160:163], v[188:191], v[118:121]
	v_mfma_f32_16x16x32_bf16 v[98:101], v[130:133], v[196:199], v[98:101]
	v_mfma_f32_16x16x32_bf16 v[102:105], v[160:163], v[196:199], v[102:105]
	s_barrier
	s_setprio 1
	v_mfma_f32_16x16x32_bf16 v[82:85], v[130:133], v[204:207], v[82:85]
	v_mfma_f32_16x16x32_bf16 v[86:89], v[160:163], v[204:207], v[86:89]
	v_mfma_f32_16x16x32_bf16 v[66:69], v[130:133], v[212:215], v[66:69]
	v_mfma_f32_16x16x32_bf16 v[70:73], v[160:163], v[212:215], v[70:73]
	v_mfma_f32_16x16x32_bf16 v[114:117], v[150:153], v[192:195], v[114:117]
	v_mfma_f32_16x16x32_bf16 v[118:121], v[164:167], v[192:195], v[118:121]
	v_mfma_f32_16x16x32_bf16 v[98:101], v[150:153], v[200:203], v[98:101]
	v_mfma_f32_16x16x32_bf16 v[102:105], v[164:167], v[200:203], v[102:105]
	v_mfma_f32_16x16x32_bf16 v[82:85], v[150:153], v[208:211], v[82:85]
	v_mfma_f32_16x16x32_bf16 v[86:89], v[164:167], v[208:211], v[86:89]
	v_mfma_f32_16x16x32_bf16 v[66:69], v[150:153], v[216:219], v[66:69]
	v_mfma_f32_16x16x32_bf16 v[70:73], v[164:167], v[216:219], v[70:73]
	v_mfma_f32_16x16x32_bf16 v[122:125], v[168:171], v[188:191], v[122:125]
	v_mfma_f32_16x16x32_bf16 v[126:129], v[180:183], v[188:191], v[126:129]
	v_mfma_f32_16x16x32_bf16 v[106:109], v[168:171], v[196:199], v[106:109]
	v_mfma_f32_16x16x32_bf16 v[110:113], v[180:183], v[196:199], v[110:113]
	v_mfma_f32_16x16x32_bf16 v[90:93], v[168:171], v[204:207], v[90:93]
	v_mfma_f32_16x16x32_bf16 v[94:97], v[180:183], v[204:207], v[94:97]
	v_mfma_f32_16x16x32_bf16 v[74:77], v[168:171], v[212:215], v[74:77]
	v_mfma_f32_16x16x32_bf16 v[78:81], v[180:183], v[212:215], v[78:81]
	v_mfma_f32_16x16x32_bf16 v[122:125], v[172:175], v[192:195], v[122:125]
	v_mfma_f32_16x16x32_bf16 v[126:129], v[184:187], v[192:195], v[126:129]
	v_mfma_f32_16x16x32_bf16 v[106:109], v[172:175], v[200:203], v[106:109]
	v_mfma_f32_16x16x32_bf16 v[110:113], v[184:187], v[200:203], v[110:113]
	v_mfma_f32_16x16x32_bf16 v[90:93], v[172:175], v[208:211], v[90:93]
	v_mfma_f32_16x16x32_bf16 v[94:97], v[184:187], v[208:211], v[94:97]
	v_mfma_f32_16x16x32_bf16 v[74:77], v[172:175], v[216:219], v[74:77]
	v_mfma_f32_16x16x32_bf16 v[78:81], v[184:187], v[216:219], v[78:81]
	s_setprio 0
	s_barrier
	s_add_i32 s46, s71, s52
	v_lshl_add_u64 v[154:155], v[154:155], 0, s[24:25]
	s_mov_b32 m0, s46
	ds_read_b128 v[188:191], v158 offset:49152
	ds_read_b128 v[192:195], v158 offset:50176
	ds_read_b128 v[196:199], v158 offset:51200
	ds_read_b128 v[200:203], v158 offset:52224
	ds_read_b128 v[204:207], v158 offset:53248
	ds_read_b128 v[208:211], v158 offset:54272
	ds_read_b128 v[212:215], v158 offset:55296
	ds_read_b128 v[216:219], v158 offset:56320
	global_load_lds_dwordx4 v[154:155], off
	s_add_i32 m0, s46, 0x2000
	s_add_u32 s44, s44, 0x40080
	v_lshl_add_u64 v[154:155], v[176:177], 0, s[24:25]
	s_addc_u32 s45, s45, 0
	s_add_i32 s46, s72, s52
	global_load_lds_dwordx4 v[154:155], off
	v_lshl_add_u64 v[154:155], s[44:45], 0, v[136:137]
	s_mov_b32 m0, s46
	s_nop 0
	global_load_lds_dwordx4 v[154:155], off
	v_lshl_add_u64 v[154:155], s[44:45], 0, v[140:141]
	s_add_i32 m0, s46, 0x2000
	s_nop 0
	global_load_lds_dwordx4 v[154:155], off
	v_lshl_add_u64 v[154:155], v[220:221], 0, s[24:25]
	s_mov_b32 m0, s59
	s_nop 0
	global_load_lds_dwordx4 v[154:155], off
	s_waitcnt vmcnt(7)
	s_waitcnt lgkmcnt(0)
	v_mfma_f32_16x16x32_bf16 v[50:53], v[130:133], v[188:191], v[50:53]
	v_mfma_f32_16x16x32_bf16 v[54:57], v[160:163], v[188:191], v[54:57]
	v_mfma_f32_16x16x32_bf16 v[26:29], v[130:133], v[196:199], v[26:29]
	v_mfma_f32_16x16x32_bf16 v[30:33], v[160:163], v[196:199], v[30:33]
	s_barrier
	s_setprio 1
	v_mfma_f32_16x16x32_bf16 v[18:21], v[130:133], v[204:207], v[18:21]
	v_mfma_f32_16x16x32_bf16 v[22:25], v[160:163], v[204:207], v[22:25]
	v_mfma_f32_16x16x32_bf16 v[2:5], v[130:133], v[212:215], v[2:5]
	v_mfma_f32_16x16x32_bf16 v[6:9], v[160:163], v[212:215], v[6:9]
	v_mfma_f32_16x16x32_bf16 v[50:53], v[150:153], v[192:195], v[50:53]
	v_mfma_f32_16x16x32_bf16 v[54:57], v[164:167], v[192:195], v[54:57]
	v_mfma_f32_16x16x32_bf16 v[26:29], v[150:153], v[200:203], v[26:29]
	v_mfma_f32_16x16x32_bf16 v[30:33], v[164:167], v[200:203], v[30:33]
	v_mfma_f32_16x16x32_bf16 v[18:21], v[150:153], v[208:211], v[18:21]
	v_mfma_f32_16x16x32_bf16 v[22:25], v[164:167], v[208:211], v[22:25]
	v_mfma_f32_16x16x32_bf16 v[2:5], v[150:153], v[216:219], v[2:5]
	v_mfma_f32_16x16x32_bf16 v[6:9], v[164:167], v[216:219], v[6:9]
	v_mfma_f32_16x16x32_bf16 v[58:61], v[168:171], v[188:191], v[58:61]
	v_mfma_f32_16x16x32_bf16 v[62:65], v[180:183], v[188:191], v[62:65]
	v_mfma_f32_16x16x32_bf16 v[42:45], v[168:171], v[196:199], v[42:45]
	v_mfma_f32_16x16x32_bf16 v[46:49], v[180:183], v[196:199], v[46:49]
	v_mfma_f32_16x16x32_bf16 v[34:37], v[168:171], v[204:207], v[34:37]
	v_mfma_f32_16x16x32_bf16 v[38:41], v[180:183], v[204:207], v[38:41]
	v_mfma_f32_16x16x32_bf16 v[10:13], v[168:171], v[212:215], v[10:13]
	v_mfma_f32_16x16x32_bf16 v[14:17], v[180:183], v[212:215], v[14:17]
	v_mfma_f32_16x16x32_bf16 v[58:61], v[172:175], v[192:195], v[58:61]
	v_mfma_f32_16x16x32_bf16 v[62:65], v[184:187], v[192:195], v[62:65]
	v_mfma_f32_16x16x32_bf16 v[42:45], v[172:175], v[200:203], v[42:45]
	v_mfma_f32_16x16x32_bf16 v[46:49], v[184:187], v[200:203], v[46:49]
	v_mfma_f32_16x16x32_bf16 v[34:37], v[172:175], v[208:211], v[34:37]
	v_mfma_f32_16x16x32_bf16 v[38:41], v[184:187], v[208:211], v[38:41]
	v_mfma_f32_16x16x32_bf16 v[10:13], v[172:175], v[216:219], v[10:13]
	v_mfma_f32_16x16x32_bf16 v[14:17], v[184:187], v[216:219], v[14:17]
	s_setprio 0
	s_barrier
	s_add_i32 s70, s70, 2
	s_add_u32 s68, s68, 0x100
	s_addc_u32 s69, s69, 0
	s_add_u32 s42, s42, 0x100
	s_addc_u32 s43, s43, 0
	s_cmp_gt_u32 s70, 13
	s_cbranch_scc0 .LBB0_1817
	v_readfirstlane_b32 s98, v178
	s_cmp_lt_u32 s98, 64
	s_cbranch_scc0 .Lkf_b
	v_readlane_b32 s98, v250, 1
	s_cmp_lg_u32 s98, 0
	s_cselect_b32 s98, 1, 0
	s_lshr_b32 s99, s81, 3
	s_cmp_lg_u32 s99, 0
	s_cselect_b32 s99, 1, 0
	s_and_b32 s98, s98, s99
	s_cbranch_scc1 .Lkf_b
	buffer_wbl2 sc1
.Lkf_b:
	s_and_b64 vcc, exec, s[26:27]
	s_cbranch_vccz .LBB0_1820
	s_barrier
.LBB0_1820:
	v_lshl_add_u32 v152, s40, 8, v1
	v_ashrrev_i32_e32 v153, 31, v152
	v_lshl_or_b32 v150, s18, 8, v157
	v_lshlrev_b64 v[154:155], 11, v[152:153]
	v_ashrrev_i32_e32 v151, 31, v150
	v_lshl_add_u64 v[154:155], s[20:21], 0, v[154:155]
	v_lshl_add_u64 v[154:155], v[150:151], 1, v[154:155]
	s_andn2_b64 vcc, exec, s[6:7]
	s_mov_b64 s[40:41], -1
	v_cvt_pk_bf16_f32 v130, v114, v115
	v_cvt_pk_bf16_f32 v131, v116, v117
	v_cvt_pk_bf16_f32 v132, v118, v119
	v_cvt_pk_bf16_f32 v133, v120, v121
	s_cbranch_vccnz .LBB0_1822
	global_store_dwordx4 v[154:155], v[130:133], off
	s_nop 1
	s_mov_b64 s[40:41], 0

.LBB0_1824:
	v_lshl_add_u64 v[154:155], v[154:155], 0, s[28:29]
	s_mov_b64 s[40:41], -1
	s_and_b64 vcc, exec, s[6:7]
	v_cvt_pk_bf16_f32 v130, v122, v123
	v_cvt_pk_bf16_f32 v131, v124, v125
	v_cvt_pk_bf16_f32 v132, v126, v127
	v_cvt_pk_bf16_f32 v133, v128, v129
	s_cbranch_vccz .LBB0_1826
	global_store_dwordx4 v[154:155], v[130:133], off
	s_nop 1
	s_mov_b64 s[40:41], 0

.LBB0_1830:
	s_or_b64 exec, exec, s[42:43]
	v_or_b32_e32 v118, 16, v152
	v_ashrrev_i32_e32 v119, 31, v118
	v_lshlrev_b64 v[120:121], 11, v[118:119]
	v_lshl_add_u64 v[120:121], s[20:21], 0, v[120:121]
	v_lshl_add_u64 v[120:121], v[150:151], 1, v[120:121]
	s_mov_b64 s[42:43], -1
	s_and_b64 vcc, exec, s[6:7]
	v_cvt_pk_bf16_f32 v114, v98, v99
	s_waitcnt lgkmcnt(0)
	v_cvt_pk_bf16_f32 v115, v100, v101
	v_cvt_pk_bf16_f32 v116, v102, v103
	v_cvt_pk_bf16_f32 v117, v104, v105
	s_cbranch_vccz .LBB0_1832
	global_store_dwordx4 v[120:121], v[114:117], off
	s_nop 1
	s_mov_b64 s[42:43], 0

.LBB0_1834:
	v_lshl_add_u64 v[120:121], v[120:121], 0, s[28:29]
	s_mov_b64 s[42:43], -1
	s_and_b64 vcc, exec, s[6:7]
	v_cvt_pk_bf16_f32 v114, v106, v107
	v_cvt_pk_bf16_f32 v115, v108, v109
	v_cvt_pk_bf16_f32 v116, v110, v111
	v_cvt_pk_bf16_f32 v117, v112, v113
	s_cbranch_vccz .LBB0_1836
	global_store_dwordx4 v[120:121], v[114:117], off
	s_nop 1
	s_mov_b64 s[42:43], 0

.LBB0_1840:
	s_or_b64 exec, exec, s[42:43]
	v_or_b32_e32 v102, 32, v152
	v_ashrrev_i32_e32 v103, 31, v102
	v_lshlrev_b64 v[104:105], 11, v[102:103]
	v_lshl_add_u64 v[104:105], s[20:21], 0, v[104:105]
	v_lshl_add_u64 v[104:105], v[150:151], 1, v[104:105]
	s_mov_b64 s[42:43], -1
	s_and_b64 vcc, exec, s[6:7]
	v_cvt_pk_bf16_f32 v98, v82, v83
	s_waitcnt lgkmcnt(0)
	v_cvt_pk_bf16_f32 v99, v84, v85
	v_cvt_pk_bf16_f32 v100, v86, v87
	v_cvt_pk_bf16_f32 v101, v88, v89
	s_cbranch_vccz .LBB0_1842
	global_store_dwordx4 v[104:105], v[98:101], off
	s_nop 1
	s_mov_b64 s[42:43], 0

.LBB0_1844:
	v_lshl_add_u64 v[104:105], v[104:105], 0, s[28:29]
	s_mov_b64 s[42:43], -1
	s_and_b64 vcc, exec, s[6:7]
	v_cvt_pk_bf16_f32 v98, v90, v91
	v_cvt_pk_bf16_f32 v99, v92, v93
	v_cvt_pk_bf16_f32 v100, v94, v95
	v_cvt_pk_bf16_f32 v101, v96, v97
	s_cbranch_vccz .LBB0_1846
	global_store_dwordx4 v[104:105], v[98:101], off
	s_nop 1
	s_mov_b64 s[42:43], 0

.LBB0_1850:
	s_or_b64 exec, exec, s[42:43]
	v_or_b32_e32 v86, 48, v152
	v_ashrrev_i32_e32 v87, 31, v86
	v_lshlrev_b64 v[88:89], 11, v[86:87]
	v_lshl_add_u64 v[88:89], s[20:21], 0, v[88:89]
	v_lshl_add_u64 v[88:89], v[150:151], 1, v[88:89]
	s_mov_b64 s[42:43], -1
	s_and_b64 vcc, exec, s[6:7]
	v_cvt_pk_bf16_f32 v82, v66, v67
	s_waitcnt lgkmcnt(0)
	v_cvt_pk_bf16_f32 v83, v68, v69
	v_cvt_pk_bf16_f32 v84, v70, v71
	v_cvt_pk_bf16_f32 v85, v72, v73
	s_cbranch_vccz .LBB0_1852
	global_store_dwordx4 v[88:89], v[82:85], off
	s_nop 1
	s_mov_b64 s[42:43], 0

.LBB0_1854:
	v_lshl_add_u64 v[88:89], v[88:89], 0, s[28:29]
	s_mov_b64 s[42:43], -1
	s_and_b64 vcc, exec, s[6:7]
	v_cvt_pk_bf16_f32 v82, v74, v75
	v_cvt_pk_bf16_f32 v83, v76, v77
	v_cvt_pk_bf16_f32 v84, v78, v79
	v_cvt_pk_bf16_f32 v85, v80, v81
	s_cbranch_vccz .LBB0_1856
	global_store_dwordx4 v[88:89], v[82:85], off
	s_nop 1
	s_mov_b64 s[42:43], 0

.LBB0_1860:
	s_or_b64 exec, exec, s[42:43]
	v_add_u32_e32 v70, 0x80, v152
	v_ashrrev_i32_e32 v71, 31, v70
	v_lshlrev_b64 v[72:73], 11, v[70:71]
	v_lshl_add_u64 v[72:73], s[20:21], 0, v[72:73]
	v_lshl_add_u64 v[72:73], v[150:151], 1, v[72:73]
	s_mov_b64 s[42:43], -1
	s_and_b64 vcc, exec, s[6:7]
	v_cvt_pk_bf16_f32 v66, v50, v51
	s_waitcnt lgkmcnt(0)
	v_cvt_pk_bf16_f32 v67, v52, v53
	v_cvt_pk_bf16_f32 v68, v54, v55
	v_cvt_pk_bf16_f32 v69, v56, v57
	s_cbranch_vccz .LBB0_1862
	global_store_dwordx4 v[72:73], v[66:69], off
	s_nop 1
	s_mov_b64 s[42:43], 0

.LBB0_1864:
	v_lshl_add_u64 v[72:73], v[72:73], 0, s[28:29]
	s_mov_b64 s[42:43], -1
	s_and_b64 vcc, exec, s[6:7]
	v_cvt_pk_bf16_f32 v66, v58, v59
	v_cvt_pk_bf16_f32 v67, v60, v61
	v_cvt_pk_bf16_f32 v68, v62, v63
	v_cvt_pk_bf16_f32 v69, v64, v65
	s_cbranch_vccz .LBB0_1866
	global_store_dwordx4 v[72:73], v[66:69], off
	s_nop 1
	s_mov_b64 s[42:43], 0

.LBB0_1870:
	s_or_b64 exec, exec, s[42:43]
	v_add_u32_e32 v54, 0x90, v152
	v_ashrrev_i32_e32 v55, 31, v54
	v_lshlrev_b64 v[56:57], 11, v[54:55]
	v_lshl_add_u64 v[56:57], s[20:21], 0, v[56:57]
	v_lshl_add_u64 v[56:57], v[150:151], 1, v[56:57]
	s_mov_b64 s[42:43], -1
	s_and_b64 vcc, exec, s[6:7]
	v_cvt_pk_bf16_f32 v50, v26, v27
	s_waitcnt lgkmcnt(0)
	v_cvt_pk_bf16_f32 v51, v28, v29
	v_cvt_pk_bf16_f32 v52, v30, v31
	v_cvt_pk_bf16_f32 v53, v32, v33
	s_cbranch_vccz .LBB0_1872
	global_store_dwordx4 v[56:57], v[50:53], off
	s_nop 1
	s_mov_b64 s[42:43], 0

.LBB0_1874:
	v_lshl_add_u64 v[56:57], v[56:57], 0, s[28:29]
	s_mov_b64 s[42:43], -1
	s_and_b64 vcc, exec, s[6:7]
	v_cvt_pk_bf16_f32 v50, v42, v43
	v_cvt_pk_bf16_f32 v51, v44, v45
	v_cvt_pk_bf16_f32 v52, v46, v47
	v_cvt_pk_bf16_f32 v53, v48, v49
	s_cbranch_vccz .LBB0_1876
	global_store_dwordx4 v[56:57], v[50:53], off
	s_nop 1
	s_mov_b64 s[42:43], 0

.LBB0_1880:
	s_or_b64 exec, exec, s[42:43]
	v_add_u32_e32 v30, 0xa0, v152
	v_ashrrev_i32_e32 v31, 31, v30
	v_lshlrev_b64 v[32:33], 11, v[30:31]
	v_lshl_add_u64 v[32:33], s[20:21], 0, v[32:33]
	v_lshl_add_u64 v[32:33], v[150:151], 1, v[32:33]
	s_mov_b64 s[42:43], -1
	s_and_b64 vcc, exec, s[6:7]
	v_cvt_pk_bf16_f32 v26, v18, v19
	s_waitcnt lgkmcnt(0)
	v_cvt_pk_bf16_f32 v27, v20, v21
	v_cvt_pk_bf16_f32 v28, v22, v23
	v_cvt_pk_bf16_f32 v29, v24, v25
	s_cbranch_vccz .LBB0_1882
	global_store_dwordx4 v[32:33], v[26:29], off
	s_nop 1
	s_mov_b64 s[42:43], 0

.LBB0_1884:
	v_lshl_add_u64 v[32:33], v[32:33], 0, s[28:29]
	s_mov_b64 s[42:43], -1
	s_and_b64 vcc, exec, s[6:7]
	v_cvt_pk_bf16_f32 v26, v34, v35
	v_cvt_pk_bf16_f32 v27, v36, v37
	v_cvt_pk_bf16_f32 v28, v38, v39
	v_cvt_pk_bf16_f32 v29, v40, v41
	s_cbranch_vccz .LBB0_1886
	global_store_dwordx4 v[32:33], v[26:29], off
	s_nop 1
	s_mov_b64 s[42:43], 0

.LBB0_1890:
	s_or_b64 exec, exec, s[42:43]
	v_add_u32_e32 v22, 0xb0, v152
	v_ashrrev_i32_e32 v23, 31, v22
	v_lshlrev_b64 v[24:25], 11, v[22:23]
	v_lshl_add_u64 v[24:25], s[20:21], 0, v[24:25]
	v_lshl_add_u64 v[24:25], v[150:151], 1, v[24:25]
	s_mov_b64 s[42:43], -1
	s_and_b64 vcc, exec, s[6:7]
	v_cvt_pk_bf16_f32 v18, v2, v3
	s_waitcnt lgkmcnt(0)
	v_cvt_pk_bf16_f32 v19, v4, v5
	v_cvt_pk_bf16_f32 v20, v6, v7
	v_cvt_pk_bf16_f32 v21, v8, v9
	s_cbranch_vccz .LBB0_1892
	global_store_dwordx4 v[24:25], v[18:21], off
	s_nop 1
	s_mov_b64 s[42:43], 0

.LBB0_1894:
	v_lshl_add_u64 v[24:25], v[24:25], 0, s[28:29]
	s_mov_b64 s[42:43], -1
	s_and_b64 vcc, exec, s[6:7]
	v_cvt_pk_bf16_f32 v18, v10, v11
	v_cvt_pk_bf16_f32 v19, v12, v13
	v_cvt_pk_bf16_f32 v20, v14, v15
	v_cvt_pk_bf16_f32 v21, v16, v17
	s_cbranch_vccz .LBB0_1896
	global_store_dwordx4 v[24:25], v[18:21], off
	s_nop 1
	s_mov_b64 s[42:43], 0
